# v10: v6 plus GU GEMM main loop issues its 16 LDS-DMA tile loads with scalar base + 32-bit lane offset (no per-load 64-bit vector add)
# baseline (speedup 1.0000x reference)
; #define PG8_STAGE(bufoff, gbase, voff) do { _Pragma("unroll") for (int _i = 0; _i < 2; ++_i) \
;         __builtin_amdgcn_global_load_lds((const unsigned*)((const char*)(gbase) + (voff)[_i]), (PG8_LAS unsigned*)(lds + (bufoff) + ldsw + _i * 8192), 16, 0, 0); } while (0)
; #define PG8_LDA(dst, b, h) do { _Pragma("unroll") for (int m = 0; m < 4; ++m) _Pragma("unroll") for (int k = 0; k < 2; ++k) dst[m][k] = *(const PG8_LAS bf16x8*)(lds + PG8_SA(b, h) + aoff + m * 2048 + k * 1024); } while (0)
; #define PG8_LDB(dst, b, h) do { _Pragma("unroll") for (int n = 0; n < 2; ++n) _Pragma("unroll") for (int k = 0; k < 2; ++k) dst[n][k] = *(const PG8_LAS bf16x8*)(lds + PG8_SB(b, h) + boff + n * 2048 + k * 1024); } while (0)
; #define PG8_MMA(ai, bj, At, Bt) do { __builtin_amdgcn_s_setprio(1); _Pragma("unroll") for (int m = 0; m < 4; ++m) _Pragma("unroll") for (int n = 0; n < 2; ++n) _Pragma("unroll") for (int k = 0; k < 2; ++k) \
;         acc[ai][bj][m][n] = __builtin_amdgcn_mfma_f32_16x16x32_bf16(Bt[n][k], At[m][k], acc[ai][bj][m][n], 0, 0, 0); __builtin_amdgcn_s_setprio(0); } while (0)
; #define PG8_BAR __builtin_amdgcn_s_barrier()
; template <class Epi, class Sched, bool ALIGN_EPI = false, bool SP2 = false>
; __device__ __forceinline__ void gemm_phase(PG8_LAS unsigned char* lds, const Gemm g, const Sched& S, const Epi& E, const int wid) {
;     ...
;             PG8_LDB(B0, 0, 0); PG8_LDB(B1, 0, 1); PG8_SCHED; PG8_LDA(At, 0, 0); PG8_STAGE(PG8_SA(1, 1), a1 + hstep, voffA);
;             PG8_WAIT_V(8); PG8_WAIT_L(0); PG8_BAR; PG8_MMA(0, 0, At, B0); PG8_MMA(0, 1, At, B1); PG8_BAR; PG8_SCHED;
;             PG8_LDA(At, 0, 1); PG8_STAGE(PG8_SB(0, 0), b2, voffB); PG8_STAGE(PG8_SB(0, 1), b2 + hstep, voffB); PG8_STAGE(PG8_SA(0, 0), a2, voffA);
;             PG8_WAIT_V(8); PG8_WAIT_L(0); PG8_BAR; PG8_MMA(1, 0, At, B0); PG8_MMA(1, 1, At, B1); PG8_BAR; PG8_SCHED;
;             PG8_LDB(B0, 1, 0); PG8_LDB(B1, 1, 1); PG8_SCHED; PG8_LDA(At, 1, 0); PG8_STAGE(PG8_SA(0, 1), a2 + hstep, voffA);
;             PG8_WAIT_V(8); PG8_WAIT_L(0); PG8_BAR; PG8_MMA(0, 0, At, B0); PG8_MMA(0, 1, At, B1); PG8_BAR; PG8_SCHED;
;             PG8_LDA(At, 1, 1); PG8_STAGE(PG8_SB(1, 0), b3, voffB); PG8_STAGE(PG8_SB(1, 1), b3 + hstep, voffB); PG8_STAGE(PG8_SA(1, 0), a3, voffA);
;             PG8_WAIT_V(8); PG8_WAIT_L(0); PG8_BAR; PG8_MMA(1, 0, At, B0); PG8_MMA(1, 1, At, B1); PG8_BAR; PG8_SCHED;
.LBB0_634:
	s_add_u32 s34, s30, 0xfff80080
	s_addc_u32 s35, s31, -1
	s_add_i32 s54, 0, 0x10000
	s_cmp_eq_u32 s50, 28
	s_cselect_b32 s37, s19, s35
	s_cselect_b32 s36, s23, s34
	v_add_u32_e32 v0, s54, v149
	s_cselect_b32 s35, s21, s47
	s_cselect_b32 s34, s29, s46
	s_add_i32 s60, 0, 0x14000
	ds_read_b128 v[142:145], v0
	ds_read_b128 v[152:155], v0 offset:1024
	ds_read_b128 v[156:159], v0 offset:2048
	ds_read_b128 v[160:163], v0 offset:3072
	v_add_u32_e32 v0, s60, v149
	ds_read_b128 v[164:167], v0
	ds_read_b128 v[168:171], v0 offset:1024
	ds_read_b128 v[172:175], v0 offset:2048
	ds_read_b128 v[176:179], v0 offset:3072
	s_add_i32 m0, s44, 0xc000
	ds_read_b128 v[180:183], v150
	ds_read_b128 v[184:187], v150 offset:1024
	ds_read_b128 v[188:191], v150 offset:2048
	ds_read_b128 v[192:195], v150 offset:3072
	ds_read_b128 v[212:215], v150 offset:4096
	ds_read_b128 v[216:219], v150 offset:5120
	ds_read_b128 v[220:223], v150 offset:6144
	ds_read_b128 v[224:227], v150 offset:7168
	global_load_lds_dwordx4 v138, s[30:31]
	s_add_i32 m0, s44, 0xe000
	s_nop 0
	global_load_lds_dwordx4 v140, s[30:31]
	s_waitcnt vmcnt(8)
	s_waitcnt lgkmcnt(0)
	s_barrier
	s_setprio 1
	s_waitcnt lgkmcnt(0)
	v_mfma_f32_16x16x32_bf16 v[126:129], v[142:145], v[180:183], v[126:129]
	v_mfma_f32_16x16x32_bf16 v[122:125], v[156:159], v[180:183], v[122:125]
	v_mfma_f32_16x16x32_bf16 v[110:113], v[142:145], v[188:191], v[110:113]
	v_mfma_f32_16x16x32_bf16 v[106:109], v[156:159], v[188:191], v[106:109]
	v_mfma_f32_16x16x32_bf16 v[94:97], v[142:145], v[212:215], v[94:97]
	v_mfma_f32_16x16x32_bf16 v[90:93], v[156:159], v[212:215], v[90:93]
	v_mfma_f32_16x16x32_bf16 v[78:81], v[142:145], v[220:223], v[78:81]
	v_mfma_f32_16x16x32_bf16 v[74:77], v[156:159], v[220:223], v[74:77]
	v_mfma_f32_16x16x32_bf16 v[126:129], v[152:155], v[184:187], v[126:129]
	v_mfma_f32_16x16x32_bf16 v[122:125], v[160:163], v[184:187], v[122:125]
	v_mfma_f32_16x16x32_bf16 v[110:113], v[152:155], v[192:195], v[110:113]
	v_mfma_f32_16x16x32_bf16 v[106:109], v[160:163], v[192:195], v[106:109]
	v_mfma_f32_16x16x32_bf16 v[94:97], v[152:155], v[216:219], v[94:97]
	v_mfma_f32_16x16x32_bf16 v[90:93], v[160:163], v[216:219], v[90:93]
	v_mfma_f32_16x16x32_bf16 v[78:81], v[152:155], v[224:227], v[78:81]
	v_mfma_f32_16x16x32_bf16 v[74:77], v[160:163], v[224:227], v[74:77]
	s_setprio 0
	s_setprio 1
	v_mfma_f32_16x16x32_bf16 v[118:121], v[164:167], v[180:183], v[118:121]
	v_mfma_f32_16x16x32_bf16 v[114:117], v[172:175], v[180:183], v[114:117]
	v_mfma_f32_16x16x32_bf16 v[102:105], v[164:167], v[188:191], v[102:105]
	v_mfma_f32_16x16x32_bf16 v[98:101], v[172:175], v[188:191], v[98:101]
	v_mfma_f32_16x16x32_bf16 v[86:89], v[164:167], v[212:215], v[86:89]
	v_mfma_f32_16x16x32_bf16 v[82:85], v[172:175], v[212:215], v[82:85]
	v_mfma_f32_16x16x32_bf16 v[70:73], v[164:167], v[220:223], v[70:73]
	v_mfma_f32_16x16x32_bf16 v[66:69], v[172:175], v[220:223], v[66:69]
	v_mfma_f32_16x16x32_bf16 v[118:121], v[168:171], v[184:187], v[118:121]
	v_mfma_f32_16x16x32_bf16 v[114:117], v[176:179], v[184:187], v[114:117]
	v_mfma_f32_16x16x32_bf16 v[102:105], v[168:171], v[192:195], v[102:105]
	v_mfma_f32_16x16x32_bf16 v[98:101], v[176:179], v[192:195], v[98:101]
	v_mfma_f32_16x16x32_bf16 v[86:89], v[168:171], v[216:219], v[86:89]
	v_mfma_f32_16x16x32_bf16 v[82:85], v[176:179], v[216:219], v[82:85]
	v_mfma_f32_16x16x32_bf16 v[70:73], v[168:171], v[224:227], v[70:73]
	v_mfma_f32_16x16x32_bf16 v[66:69], v[176:179], v[224:227], v[66:69]
	s_setprio 0
	s_barrier
	s_add_i32 s54, s54, s42
	s_mov_b32 m0, s54
	ds_read_b128 v[180:183], v150 offset:16384
	ds_read_b128 v[184:187], v150 offset:17408
	ds_read_b128 v[188:191], v150 offset:18432
	ds_read_b128 v[192:195], v150 offset:19456
	ds_read_b128 v[212:215], v150 offset:20480
	ds_read_b128 v[216:219], v150 offset:21504
	ds_read_b128 v[220:223], v150 offset:22528
	ds_read_b128 v[224:227], v150 offset:23552
	global_load_lds_dwordx4 v134, s[34:35]
	s_add_i32 m0, s54, 0x2000
	s_add_u32 s54, s34, 0x80000
	s_addc_u32 s55, s35, 0
	s_add_i32 s60, s60, s42
	global_load_lds_dwordx4 v130, s[34:35]
	s_mov_b32 m0, s60
	s_nop 0
	global_load_lds_dwordx4 v134, s[54:55]
	s_add_i32 m0, s60, 0x2000
	s_nop 0
	global_load_lds_dwordx4 v130, s[54:55]
	s_mov_b32 m0, s44
	s_nop 0
	global_load_lds_dwordx4 v136, s[36:37]
	s_mov_b32 m0, s45
	s_nop 0
	global_load_lds_dwordx4 v132, s[36:37]
	s_waitcnt vmcnt(8)
	s_waitcnt lgkmcnt(0)
	s_barrier
	s_setprio 1
	s_waitcnt lgkmcnt(0)
	v_mfma_f32_16x16x32_bf16 v[62:65], v[142:145], v[180:183], v[62:65]
	v_mfma_f32_16x16x32_bf16 v[58:61], v[156:159], v[180:183], v[58:61]
	v_mfma_f32_16x16x32_bf16 v[46:49], v[142:145], v[188:191], v[46:49]
	v_mfma_f32_16x16x32_bf16 v[42:45], v[156:159], v[188:191], v[42:45]
	v_mfma_f32_16x16x32_bf16 v[30:33], v[142:145], v[212:215], v[30:33]
	v_mfma_f32_16x16x32_bf16 v[26:29], v[156:159], v[212:215], v[26:29]
	v_mfma_f32_16x16x32_bf16 v[14:17], v[142:145], v[220:223], v[14:17]
	v_mfma_f32_16x16x32_bf16 v[10:13], v[156:159], v[220:223], v[10:13]
	v_mfma_f32_16x16x32_bf16 v[62:65], v[152:155], v[184:187], v[62:65]
	v_mfma_f32_16x16x32_bf16 v[58:61], v[160:163], v[184:187], v[58:61]
	v_mfma_f32_16x16x32_bf16 v[46:49], v[152:155], v[192:195], v[46:49]
	v_mfma_f32_16x16x32_bf16 v[42:45], v[160:163], v[192:195], v[42:45]
	v_mfma_f32_16x16x32_bf16 v[30:33], v[152:155], v[216:219], v[30:33]
	v_mfma_f32_16x16x32_bf16 v[26:29], v[160:163], v[216:219], v[26:29]
	v_mfma_f32_16x16x32_bf16 v[14:17], v[152:155], v[224:227], v[14:17]
	v_mfma_f32_16x16x32_bf16 v[10:13], v[160:163], v[224:227], v[10:13]
	s_setprio 0
	s_setprio 1
	v_mfma_f32_16x16x32_bf16 v[54:57], v[164:167], v[180:183], v[54:57]
	v_mfma_f32_16x16x32_bf16 v[50:53], v[172:175], v[180:183], v[50:53]
	v_mfma_f32_16x16x32_bf16 v[38:41], v[164:167], v[188:191], v[38:41]
	v_mfma_f32_16x16x32_bf16 v[34:37], v[172:175], v[188:191], v[34:37]
	v_mfma_f32_16x16x32_bf16 v[22:25], v[164:167], v[212:215], v[22:25]
	v_mfma_f32_16x16x32_bf16 v[18:21], v[172:175], v[212:215], v[18:21]
	v_mfma_f32_16x16x32_bf16 v[6:9], v[164:167], v[220:223], v[6:9]
	v_mfma_f32_16x16x32_bf16 v[2:5], v[172:175], v[220:223], v[2:5]
	v_mfma_f32_16x16x32_bf16 v[54:57], v[168:171], v[184:187], v[54:57]
	v_mfma_f32_16x16x32_bf16 v[50:53], v[176:179], v[184:187], v[50:53]
	v_mfma_f32_16x16x32_bf16 v[38:41], v[168:171], v[192:195], v[38:41]
	v_mfma_f32_16x16x32_bf16 v[34:37], v[176:179], v[192:195], v[34:37]
	v_mfma_f32_16x16x32_bf16 v[22:25], v[168:171], v[216:219], v[22:25]
	v_mfma_f32_16x16x32_bf16 v[18:21], v[176:179], v[216:219], v[18:21]
	v_mfma_f32_16x16x32_bf16 v[6:9], v[168:171], v[224:227], v[6:9]
	v_mfma_f32_16x16x32_bf16 v[2:5], v[176:179], v[224:227], v[2:5]
	s_setprio 0
	s_barrier
; #define PG8_STAGE(bufoff, gbase, voff) do { _Pragma("unroll") for (int _i = 0; _i < 2; ++_i) \
;         __builtin_amdgcn_global_load_lds((const unsigned*)((const char*)(gbase) + (voff)[_i]), (PG8_LAS unsigned*)(lds + (bufoff) + ldsw + _i * 8192), 16, 0, 0); } while (0)
; #define PG8_LDA(dst, b, h) do { _Pragma("unroll") for (int m = 0; m < 4; ++m) _Pragma("unroll") for (int k = 0; k < 2; ++k) dst[m][k] = *(const PG8_LAS bf16x8*)(lds + PG8_SA(b, h) + aoff + m * 2048 + k * 1024); } while (0)
; #define PG8_LDB(dst, b, h) do { _Pragma("unroll") for (int n = 0; n < 2; ++n) _Pragma("unroll") for (int k = 0; k < 2; ++k) dst[n][k] = *(const PG8_LAS bf16x8*)(lds + PG8_SB(b, h) + boff + n * 2048 + k * 1024); } while (0)
; #define PG8_MMA(ai, bj, At, Bt) do { __builtin_amdgcn_s_setprio(1); _Pragma("unroll") for (int m = 0; m < 4; ++m) _Pragma("unroll") for (int n = 0; n < 2; ++n) _Pragma("unroll") for (int k = 0; k < 2; ++k) \
;         acc[ai][bj][m][n] = __builtin_amdgcn_mfma_f32_16x16x32_bf16(Bt[n][k], At[m][k], acc[ai][bj][m][n], 0, 0, 0); __builtin_amdgcn_s_setprio(0); } while (0)
; #define PG8_BAR __builtin_amdgcn_s_barrier()
; template <class Epi, class Sched, bool ALIGN_EPI = false, bool SP2 = false>
; __device__ __forceinline__ void gemm_phase(PG8_LAS unsigned char* lds, const Gemm g, const Sched& S, const Epi& E, const int wid) {
;     ...
;             PG8_LDB(B0, 0, 0); PG8_LDB(B1, 0, 1); PG8_SCHED; PG8_LDA(At, 0, 0); PG8_STAGE(PG8_SA(1, 1), a1 + hstep, voffA);
;             PG8_WAIT_V(8); PG8_WAIT_L(0); PG8_BAR; PG8_MMA(0, 0, At, B0); PG8_MMA(0, 1, At, B1); PG8_BAR; PG8_SCHED;
;             PG8_LDA(At, 0, 1); PG8_STAGE(PG8_SB(0, 0), b2, voffB); PG8_STAGE(PG8_SB(0, 1), b2 + hstep, voffB); PG8_STAGE(PG8_SA(0, 0), a2, voffA);
;             PG8_WAIT_V(8); PG8_WAIT_L(0); PG8_BAR; PG8_MMA(1, 0, At, B0); PG8_MMA(1, 1, At, B1); PG8_BAR; PG8_SCHED;
;             PG8_LDB(B0, 1, 0); PG8_LDB(B1, 1, 1); PG8_SCHED; PG8_LDA(At, 1, 0); PG8_STAGE(PG8_SA(0, 1), a2 + hstep, voffA);
;             PG8_WAIT_V(8); PG8_WAIT_L(0); PG8_BAR; PG8_MMA(0, 0, At, B0); PG8_MMA(0, 1, At, B1); PG8_BAR; PG8_SCHED;
;             PG8_LDA(At, 1, 1); PG8_STAGE(PG8_SB(1, 0), b3, voffB); PG8_STAGE(PG8_SB(1, 1), b3 + hstep, voffB); PG8_STAGE(PG8_SA(1, 0), a3, voffA);
;             PG8_WAIT_V(8); PG8_WAIT_L(0); PG8_BAR; PG8_MMA(1, 0, At, B0); PG8_MMA(1, 1, At, B1); PG8_BAR; PG8_SCHED;
	s_add_i32 s54, 0, 0x18000
	v_add_u32_e32 v0, s54, v149
	s_add_i32 s55, 0, 0x1c000
	ds_read_b128 v[142:145], v0
	ds_read_b128 v[152:155], v0 offset:1024
	ds_read_b128 v[156:159], v0 offset:2048
	ds_read_b128 v[160:163], v0 offset:3072
	v_add_u32_e32 v0, s55, v149
	ds_read_b128 v[164:167], v0
	ds_read_b128 v[168:171], v0 offset:1024
	ds_read_b128 v[172:175], v0 offset:2048
	ds_read_b128 v[176:179], v0 offset:3072
	s_add_u32 s36, s36, 0x80000
	s_addc_u32 s37, s37, 0
	s_add_u32 s100, s36, 0xfff80080
	s_addc_u32 s101, s37, -1
	s_mov_b32 m0, s52
	ds_read_b128 v[180:183], v150 offset:32768
	ds_read_b128 v[184:187], v150 offset:33792
	ds_read_b128 v[188:191], v150 offset:34816
	ds_read_b128 v[192:195], v150 offset:35840
	ds_read_b128 v[212:215], v150 offset:36864
	ds_read_b128 v[216:219], v150 offset:37888
	ds_read_b128 v[220:223], v150 offset:38912
	ds_read_b128 v[224:227], v150 offset:39936
	global_load_lds_dwordx4 v136, s[36:37]
	s_mov_b32 m0, s68
	s_nop 0
	global_load_lds_dwordx4 v132, s[36:37]
	s_waitcnt vmcnt(8)
	s_waitcnt lgkmcnt(0)
	s_barrier
	s_setprio 1
	s_waitcnt lgkmcnt(0)
	v_mfma_f32_16x16x32_bf16 v[126:129], v[142:145], v[180:183], v[126:129]
	v_mfma_f32_16x16x32_bf16 v[122:125], v[156:159], v[180:183], v[122:125]
	v_mfma_f32_16x16x32_bf16 v[110:113], v[142:145], v[188:191], v[110:113]
	v_mfma_f32_16x16x32_bf16 v[106:109], v[156:159], v[188:191], v[106:109]
	v_mfma_f32_16x16x32_bf16 v[94:97], v[142:145], v[212:215], v[94:97]
	v_mfma_f32_16x16x32_bf16 v[90:93], v[156:159], v[212:215], v[90:93]
	v_mfma_f32_16x16x32_bf16 v[78:81], v[142:145], v[220:223], v[78:81]
	v_mfma_f32_16x16x32_bf16 v[74:77], v[156:159], v[220:223], v[74:77]
	v_mfma_f32_16x16x32_bf16 v[126:129], v[152:155], v[184:187], v[126:129]
	v_mfma_f32_16x16x32_bf16 v[122:125], v[160:163], v[184:187], v[122:125]
	v_mfma_f32_16x16x32_bf16 v[110:113], v[152:155], v[192:195], v[110:113]
	v_mfma_f32_16x16x32_bf16 v[106:109], v[160:163], v[192:195], v[106:109]
	v_mfma_f32_16x16x32_bf16 v[94:97], v[152:155], v[216:219], v[94:97]
	v_mfma_f32_16x16x32_bf16 v[90:93], v[160:163], v[216:219], v[90:93]
	v_mfma_f32_16x16x32_bf16 v[78:81], v[152:155], v[224:227], v[78:81]
	v_mfma_f32_16x16x32_bf16 v[74:77], v[160:163], v[224:227], v[74:77]
	s_setprio 0
	s_setprio 1
	v_mfma_f32_16x16x32_bf16 v[118:121], v[164:167], v[180:183], v[118:121]
	v_mfma_f32_16x16x32_bf16 v[114:117], v[172:175], v[180:183], v[114:117]
	v_mfma_f32_16x16x32_bf16 v[102:105], v[164:167], v[188:191], v[102:105]
	v_mfma_f32_16x16x32_bf16 v[98:101], v[172:175], v[188:191], v[98:101]
	v_mfma_f32_16x16x32_bf16 v[86:89], v[164:167], v[212:215], v[86:89]
	v_mfma_f32_16x16x32_bf16 v[82:85], v[172:175], v[212:215], v[82:85]
	v_mfma_f32_16x16x32_bf16 v[70:73], v[164:167], v[220:223], v[70:73]
	v_mfma_f32_16x16x32_bf16 v[66:69], v[172:175], v[220:223], v[66:69]
	v_mfma_f32_16x16x32_bf16 v[118:121], v[168:171], v[184:187], v[118:121]
	v_mfma_f32_16x16x32_bf16 v[114:117], v[176:179], v[184:187], v[114:117]
	v_mfma_f32_16x16x32_bf16 v[102:105], v[168:171], v[192:195], v[102:105]
	v_mfma_f32_16x16x32_bf16 v[98:101], v[176:179], v[192:195], v[98:101]
	v_mfma_f32_16x16x32_bf16 v[86:89], v[168:171], v[216:219], v[86:89]
	v_mfma_f32_16x16x32_bf16 v[82:85], v[176:179], v[216:219], v[82:85]
	v_mfma_f32_16x16x32_bf16 v[70:73], v[168:171], v[224:227], v[70:73]
	v_mfma_f32_16x16x32_bf16 v[66:69], v[176:179], v[224:227], v[66:69]
	s_setprio 0
	s_barrier
	s_add_i32 s36, s54, s42
	s_add_u32 s34, s34, 0x80
	s_addc_u32 s35, s35, 0
	s_mov_b32 m0, s36
	ds_read_b128 v[180:183], v150 offset:49152
	ds_read_b128 v[184:187], v150 offset:50176
	ds_read_b128 v[188:191], v150 offset:51200
	ds_read_b128 v[192:195], v150 offset:52224
	ds_read_b128 v[212:215], v150 offset:53248
	ds_read_b128 v[216:219], v150 offset:54272
	ds_read_b128 v[220:223], v150 offset:55296
	ds_read_b128 v[224:227], v150 offset:56320
	global_load_lds_dwordx4 v134, s[34:35]
	s_add_i32 m0, s36, 0x2000
	s_add_i32 s36, s55, s42
	global_load_lds_dwordx4 v130, s[34:35]
	s_add_u32 s34, s34, 0x80000
	s_addc_u32 s35, s35, 0
	s_mov_b32 m0, s36
	s_nop 0
	global_load_lds_dwordx4 v134, s[34:35]
	s_add_i32 m0, s36, 0x2000
	s_nop 0
	global_load_lds_dwordx4 v130, s[34:35]
	s_mov_b32 m0, s84
	s_nop 0
	global_load_lds_dwordx4 v136, s[100:101]
	s_mov_b32 m0, s85
	s_nop 0
	global_load_lds_dwordx4 v132, s[100:101]
	s_waitcnt vmcnt(8)
	s_waitcnt lgkmcnt(0)
	s_barrier
	s_setprio 1
	s_waitcnt lgkmcnt(0)
	v_mfma_f32_16x16x32_bf16 v[62:65], v[142:145], v[180:183], v[62:65]
	v_mfma_f32_16x16x32_bf16 v[58:61], v[156:159], v[180:183], v[58:61]
	v_mfma_f32_16x16x32_bf16 v[46:49], v[142:145], v[188:191], v[46:49]
	v_mfma_f32_16x16x32_bf16 v[42:45], v[156:159], v[188:191], v[42:45]
	v_mfma_f32_16x16x32_bf16 v[30:33], v[142:145], v[212:215], v[30:33]
	v_mfma_f32_16x16x32_bf16 v[26:29], v[156:159], v[212:215], v[26:29]
	v_mfma_f32_16x16x32_bf16 v[14:17], v[142:145], v[220:223], v[14:17]
	v_mfma_f32_16x16x32_bf16 v[10:13], v[156:159], v[220:223], v[10:13]
	v_mfma_f32_16x16x32_bf16 v[62:65], v[152:155], v[184:187], v[62:65]
	v_mfma_f32_16x16x32_bf16 v[58:61], v[160:163], v[184:187], v[58:61]
	v_mfma_f32_16x16x32_bf16 v[46:49], v[152:155], v[192:195], v[46:49]
	v_mfma_f32_16x16x32_bf16 v[42:45], v[160:163], v[192:195], v[42:45]
	v_mfma_f32_16x16x32_bf16 v[30:33], v[152:155], v[216:219], v[30:33]
	v_mfma_f32_16x16x32_bf16 v[26:29], v[160:163], v[216:219], v[26:29]
	v_mfma_f32_16x16x32_bf16 v[14:17], v[152:155], v[224:227], v[14:17]
	v_mfma_f32_16x16x32_bf16 v[10:13], v[160:163], v[224:227], v[10:13]
	s_setprio 0
	s_setprio 1
	v_mfma_f32_16x16x32_bf16 v[54:57], v[164:167], v[180:183], v[54:57]
	v_mfma_f32_16x16x32_bf16 v[50:53], v[172:175], v[180:183], v[50:53]
	v_mfma_f32_16x16x32_bf16 v[38:41], v[164:167], v[188:191], v[38:41]
	v_mfma_f32_16x16x32_bf16 v[34:37], v[172:175], v[188:191], v[34:37]
	v_mfma_f32_16x16x32_bf16 v[22:25], v[164:167], v[212:215], v[22:25]
	v_mfma_f32_16x16x32_bf16 v[18:21], v[172:175], v[212:215], v[18:21]
	v_mfma_f32_16x16x32_bf16 v[6:9], v[164:167], v[220:223], v[6:9]
	v_mfma_f32_16x16x32_bf16 v[2:5], v[172:175], v[220:223], v[2:5]
	v_mfma_f32_16x16x32_bf16 v[54:57], v[168:171], v[184:187], v[54:57]
	v_mfma_f32_16x16x32_bf16 v[50:53], v[176:179], v[184:187], v[50:53]
	v_mfma_f32_16x16x32_bf16 v[38:41], v[168:171], v[192:195], v[38:41]
	v_mfma_f32_16x16x32_bf16 v[34:37], v[176:179], v[192:195], v[34:37]
	v_mfma_f32_16x16x32_bf16 v[22:25], v[168:171], v[216:219], v[22:25]
	v_mfma_f32_16x16x32_bf16 v[18:21], v[176:179], v[216:219], v[18:21]
	v_mfma_f32_16x16x32_bf16 v[6:9], v[168:171], v[224:227], v[6:9]
	v_mfma_f32_16x16x32_bf16 v[2:5], v[176:179], v[224:227], v[2:5]
	s_setprio 0
	s_barrier
	s_add_i32 s50, s50, 2
	s_add_u32 s30, s30, 0x100
	s_addc_u32 s31, s31, 0
	s_add_u32 s46, s46, 0x100
	s_addc_u32 s47, s47, 0
	s_cmp_gt_u32 s50, 29
	s_cbranch_scc0 .LBB0_634
	s_and_b64 vcc, exec, s[16:17]
	s_cbranch_vccz .LBB0_637
	s_barrier
